# accumulator zeroing: dropped hipcc's duplicate zero block per unit, 64-bit moves for the remaining one
# speedup vs baseline: 1.0840x; 1.0150x over previous
; template <class Epi, class Sched, bool ALIGN_EPI = false, bool SP2 = false>
; __device__ __forceinline__ void gemm_phase(PG8_LAS unsigned char* lds, const Gemm g, const Sched& S, const Epi& E) {
;     ...
; #pragma unroll
;         for (int a = 0; a < 2; ++a)
; #pragma unroll
;             for (int b = 0; b < 2; ++b)
; #pragma unroll
;                 for (int m = 0; m < 4; ++m)
; #pragma unroll
;                     for (int n = 0; n < 2; ++n) acc[a][b][m][n] = (f32x4){0.f, 0.f, 0.f, 0.f};
.LBB0_262:
	v_mov_b64_e32 v[0:1], 0
	v_mov_b64_e32 v[2:3], 0
	v_mov_b64_e32 v[4:5], 0
	v_mov_b64_e32 v[6:7], 0
	v_mov_b64_e32 v[8:9], 0
	v_mov_b64_e32 v[10:11], 0
	v_mov_b64_e32 v[12:13], 0
	v_mov_b64_e32 v[14:15], 0
	v_mov_b64_e32 v[16:17], 0
	v_mov_b64_e32 v[18:19], 0
	v_mov_b64_e32 v[20:21], 0
	v_mov_b64_e32 v[22:23], 0
	v_mov_b64_e32 v[24:25], 0
	v_mov_b64_e32 v[26:27], 0
	v_mov_b64_e32 v[28:29], 0
	v_mov_b64_e32 v[30:31], 0
	v_mov_b64_e32 v[32:33], 0
	v_mov_b64_e32 v[34:35], 0
	v_mov_b64_e32 v[36:37], 0
	v_mov_b64_e32 v[38:39], 0
	v_mov_b64_e32 v[40:41], 0
	v_mov_b64_e32 v[42:43], 0
	v_mov_b64_e32 v[44:45], 0
	v_mov_b64_e32 v[46:47], 0
	v_mov_b64_e32 v[48:49], 0
	v_mov_b64_e32 v[50:51], 0
	v_mov_b64_e32 v[52:53], 0
	v_mov_b64_e32 v[54:55], 0
	v_mov_b64_e32 v[56:57], 0
	v_mov_b64_e32 v[58:59], 0
	v_mov_b64_e32 v[60:61], 0
	v_mov_b64_e32 v[62:63], 0
	v_mov_b64_e32 v[64:65], 0
	v_mov_b64_e32 v[66:67], 0
	v_mov_b64_e32 v[68:69], 0
	v_mov_b64_e32 v[70:71], 0
	v_mov_b64_e32 v[72:73], 0
	v_mov_b64_e32 v[74:75], 0
	v_mov_b64_e32 v[76:77], 0
	v_mov_b64_e32 v[78:79], 0
	v_mov_b64_e32 v[80:81], 0
	v_mov_b64_e32 v[82:83], 0
	v_mov_b64_e32 v[84:85], 0
	v_mov_b64_e32 v[86:87], 0
	v_mov_b64_e32 v[88:89], 0
	v_mov_b64_e32 v[90:91], 0
	v_mov_b64_e32 v[92:93], 0
	v_mov_b64_e32 v[94:95], 0
	v_mov_b64_e32 v[96:97], 0
	v_mov_b64_e32 v[98:99], 0
	v_mov_b64_e32 v[100:101], 0
	v_mov_b64_e32 v[102:103], 0
	v_mov_b64_e32 v[104:105], 0
	v_mov_b64_e32 v[106:107], 0
	v_mov_b64_e32 v[108:109], 0
	v_mov_b64_e32 v[110:111], 0
	v_mov_b64_e32 v[112:113], 0
	v_mov_b64_e32 v[114:115], 0
	v_mov_b64_e32 v[116:117], 0
	v_mov_b64_e32 v[118:119], 0
	v_mov_b64_e32 v[120:121], 0
	v_mov_b64_e32 v[122:123], 0
	v_mov_b64_e32 v[124:125], 0
	v_mov_b64_e32 v[126:127], 0
	s_andn2_b64 vcc, exec, s[20:21]
	s_waitcnt vmcnt(0)
	s_waitcnt lgkmcnt(0)
	.p2align 8
	s_cbranch_vccnz .LBB0_265
	s_add_u32 s40, s40, 0x80
	s_addc_u32 s41, s41, 0
	s_add_u32 s33, s42, 0x100
	s_addc_u32 s38, s43, 0
	s_mov_b32 s42, 0

; template <class Epi, class Sched, bool ALIGN_EPI = false, bool SP2 = false>
; __device__ __forceinline__ void gemm_phase(PG8_LAS unsigned char* lds, const Gemm g, const Sched& S, const Epi& E) {
;     ...
; #pragma unroll
;         for (int a = 0; a < 2; ++a)
; #pragma unroll
;             for (int b = 0; b < 2; ++b)
; #pragma unroll
;                 for (int m = 0; m < 4; ++m)
; #pragma unroll
;                     for (int n = 0; n < 2; ++n) acc[a][b][m][n] = (f32x4){0.f, 0.f, 0.f, 0.f};
.LBB0_282:
	v_mov_b64_e32 v[0:1], 0
	v_mov_b64_e32 v[2:3], 0
	v_mov_b64_e32 v[4:5], 0
	v_mov_b64_e32 v[6:7], 0
	v_mov_b64_e32 v[8:9], 0
	v_mov_b64_e32 v[10:11], 0
	v_mov_b64_e32 v[12:13], 0
	v_mov_b64_e32 v[14:15], 0
	v_mov_b64_e32 v[16:17], 0
	v_mov_b64_e32 v[18:19], 0
	v_mov_b64_e32 v[20:21], 0
	v_mov_b64_e32 v[22:23], 0
	v_mov_b64_e32 v[24:25], 0
	v_mov_b64_e32 v[26:27], 0
	v_mov_b64_e32 v[28:29], 0
	v_mov_b64_e32 v[30:31], 0
	v_mov_b64_e32 v[32:33], 0
	v_mov_b64_e32 v[34:35], 0
	v_mov_b64_e32 v[36:37], 0
	v_mov_b64_e32 v[38:39], 0
	v_mov_b64_e32 v[40:41], 0
	v_mov_b64_e32 v[42:43], 0
	v_mov_b64_e32 v[44:45], 0
	v_mov_b64_e32 v[46:47], 0
	v_mov_b64_e32 v[48:49], 0
	v_mov_b64_e32 v[50:51], 0
	v_mov_b64_e32 v[52:53], 0
	v_mov_b64_e32 v[54:55], 0
	v_mov_b64_e32 v[56:57], 0
	v_mov_b64_e32 v[58:59], 0
	v_mov_b64_e32 v[60:61], 0
	v_mov_b64_e32 v[62:63], 0
	v_mov_b64_e32 v[64:65], 0
	v_mov_b64_e32 v[66:67], 0
	v_mov_b64_e32 v[68:69], 0
	v_mov_b64_e32 v[70:71], 0
	v_mov_b64_e32 v[72:73], 0
	v_mov_b64_e32 v[74:75], 0
	v_mov_b64_e32 v[76:77], 0
	v_mov_b64_e32 v[78:79], 0
	v_mov_b64_e32 v[80:81], 0
	v_mov_b64_e32 v[82:83], 0
	v_mov_b64_e32 v[84:85], 0
	v_mov_b64_e32 v[86:87], 0
	v_mov_b64_e32 v[88:89], 0
	v_mov_b64_e32 v[90:91], 0
	v_mov_b64_e32 v[92:93], 0
	v_mov_b64_e32 v[94:95], 0
	v_mov_b64_e32 v[96:97], 0
	v_mov_b64_e32 v[98:99], 0
	v_mov_b64_e32 v[100:101], 0
	v_mov_b64_e32 v[102:103], 0
	v_mov_b64_e32 v[104:105], 0
	v_mov_b64_e32 v[106:107], 0
	v_mov_b64_e32 v[108:109], 0
	v_mov_b64_e32 v[110:111], 0
	v_mov_b64_e32 v[112:113], 0
	v_mov_b64_e32 v[114:115], 0
	v_mov_b64_e32 v[116:117], 0
	v_mov_b64_e32 v[118:119], 0
	v_mov_b64_e32 v[120:121], 0
	v_mov_b64_e32 v[122:123], 0
	v_mov_b64_e32 v[124:125], 0
	v_mov_b64_e32 v[126:127], 0
	s_and_b64 vcc, exec, s[6:7]
	s_waitcnt lgkmcnt(0)
	.p2align 8
	s_cbranch_vccnz .LBB0_285
	s_add_u32 s60, s60, 0x80
	s_addc_u32 s61, s61, 0
	s_add_u32 s33, s62, 0x100
	s_addc_u32 s89, s63, 0
	s_mov_b32 s62, 0

; template <class Epi, class Sched, bool ALIGN_EPI = false, bool SP2 = false>
; __device__ __forceinline__ void gemm_phase(PG8_LAS unsigned char* lds, const Gemm g, const Sched& S, const Epi& E) {
;     ...
; #pragma unroll
;         for (int a = 0; a < 2; ++a)
; #pragma unroll
;             for (int b = 0; b < 2; ++b)
; #pragma unroll
;                 for (int m = 0; m < 4; ++m)
; #pragma unroll
;                     for (int n = 0; n < 2; ++n) acc[a][b][m][n] = (f32x4){0.f, 0.f, 0.f, 0.f};
.LBB0_471:
	v_mov_b64_e32 v[0:1], 0
	v_mov_b64_e32 v[2:3], 0
	v_mov_b64_e32 v[4:5], 0
	v_mov_b64_e32 v[6:7], 0
	v_mov_b64_e32 v[8:9], 0
	v_mov_b64_e32 v[10:11], 0
	v_mov_b64_e32 v[12:13], 0
	v_mov_b64_e32 v[14:15], 0
	v_mov_b64_e32 v[16:17], 0
	v_mov_b64_e32 v[18:19], 0
	v_mov_b64_e32 v[20:21], 0
	v_mov_b64_e32 v[22:23], 0
	v_mov_b64_e32 v[24:25], 0
	v_mov_b64_e32 v[26:27], 0
	v_mov_b64_e32 v[28:29], 0
	v_mov_b64_e32 v[30:31], 0
	v_mov_b64_e32 v[32:33], 0
	v_mov_b64_e32 v[34:35], 0
	v_mov_b64_e32 v[36:37], 0
	v_mov_b64_e32 v[38:39], 0
	v_mov_b64_e32 v[40:41], 0
	v_mov_b64_e32 v[42:43], 0
	v_mov_b64_e32 v[44:45], 0
	v_mov_b64_e32 v[46:47], 0
	v_mov_b64_e32 v[48:49], 0
	v_mov_b64_e32 v[50:51], 0
	v_mov_b64_e32 v[52:53], 0
	v_mov_b64_e32 v[54:55], 0
	v_mov_b64_e32 v[56:57], 0
	v_mov_b64_e32 v[58:59], 0
	v_mov_b64_e32 v[60:61], 0
	v_mov_b64_e32 v[62:63], 0
	v_mov_b64_e32 v[64:65], 0
	v_mov_b64_e32 v[66:67], 0
	v_mov_b64_e32 v[68:69], 0
	v_mov_b64_e32 v[70:71], 0
	v_mov_b64_e32 v[72:73], 0
	v_mov_b64_e32 v[74:75], 0
	v_mov_b64_e32 v[76:77], 0
	v_mov_b64_e32 v[78:79], 0
	v_mov_b64_e32 v[80:81], 0
	v_mov_b64_e32 v[82:83], 0
	v_mov_b64_e32 v[84:85], 0
	v_mov_b64_e32 v[86:87], 0
	v_mov_b64_e32 v[88:89], 0
	v_mov_b64_e32 v[90:91], 0
	v_mov_b64_e32 v[92:93], 0
	v_mov_b64_e32 v[94:95], 0
	v_mov_b64_e32 v[96:97], 0
	v_mov_b64_e32 v[98:99], 0
	v_mov_b64_e32 v[100:101], 0
	v_mov_b64_e32 v[102:103], 0
	v_mov_b64_e32 v[104:105], 0
	v_mov_b64_e32 v[106:107], 0
	v_mov_b64_e32 v[108:109], 0
	v_mov_b64_e32 v[110:111], 0
	v_mov_b64_e32 v[112:113], 0
	v_mov_b64_e32 v[114:115], 0
	v_mov_b64_e32 v[116:117], 0
	v_mov_b64_e32 v[118:119], 0
	v_mov_b64_e32 v[120:121], 0
	v_mov_b64_e32 v[122:123], 0
	v_mov_b64_e32 v[124:125], 0
	v_mov_b64_e32 v[126:127], 0
	s_andn2_b64 vcc, exec, s[56:57]
	s_waitcnt vmcnt(0)
	s_waitcnt lgkmcnt(0)
	.p2align 8
	s_cbranch_vccnz .LBB0_474
	s_add_u32 s10, s14, 0x80
	s_addc_u32 s11, s15, 0
	s_add_u32 s5, s12, 0x100
	s_addc_u32 s14, s13, 0
	s_mov_b32 s12, 0

; template <class Epi, class Sched, bool ALIGN_EPI = false, bool SP2 = false>
; __device__ __forceinline__ void gemm_phase(PG8_LAS unsigned char* lds, const Gemm g, const Sched& S, const Epi& E) {
;     ...
; #pragma unroll
;         for (int a = 0; a < 2; ++a)
; #pragma unroll
;             for (int b = 0; b < 2; ++b)
; #pragma unroll
;                 for (int m = 0; m < 4; ++m)
; #pragma unroll
;                     for (int n = 0; n < 2; ++n) acc[a][b][m][n] = (f32x4){0.f, 0.f, 0.f, 0.f};
.LBB0_631:
	v_mov_b64_e32 v[0:1], 0
	v_mov_b64_e32 v[2:3], 0
	v_mov_b64_e32 v[4:5], 0
	v_mov_b64_e32 v[6:7], 0
	v_mov_b64_e32 v[8:9], 0
	v_mov_b64_e32 v[10:11], 0
	v_mov_b64_e32 v[12:13], 0
	v_mov_b64_e32 v[14:15], 0
	v_mov_b64_e32 v[16:17], 0
	v_mov_b64_e32 v[18:19], 0
	v_mov_b64_e32 v[20:21], 0
	v_mov_b64_e32 v[22:23], 0
	v_mov_b64_e32 v[24:25], 0
	v_mov_b64_e32 v[26:27], 0
	v_mov_b64_e32 v[28:29], 0
	v_mov_b64_e32 v[30:31], 0
	v_mov_b64_e32 v[32:33], 0
	v_mov_b64_e32 v[34:35], 0
	v_mov_b64_e32 v[36:37], 0
	v_mov_b64_e32 v[38:39], 0
	v_mov_b64_e32 v[40:41], 0
	v_mov_b64_e32 v[42:43], 0
	v_mov_b64_e32 v[44:45], 0
	v_mov_b64_e32 v[46:47], 0
	v_mov_b64_e32 v[48:49], 0
	v_mov_b64_e32 v[50:51], 0
	v_mov_b64_e32 v[52:53], 0
	v_mov_b64_e32 v[54:55], 0
	v_mov_b64_e32 v[56:57], 0
	v_mov_b64_e32 v[58:59], 0
	v_mov_b64_e32 v[60:61], 0
	v_mov_b64_e32 v[62:63], 0
	v_mov_b64_e32 v[64:65], 0
	v_mov_b64_e32 v[66:67], 0
	v_mov_b64_e32 v[68:69], 0
	v_mov_b64_e32 v[70:71], 0
	v_mov_b64_e32 v[72:73], 0
	v_mov_b64_e32 v[74:75], 0
	v_mov_b64_e32 v[76:77], 0
	v_mov_b64_e32 v[78:79], 0
	v_mov_b64_e32 v[80:81], 0
	v_mov_b64_e32 v[82:83], 0
	v_mov_b64_e32 v[84:85], 0
	v_mov_b64_e32 v[86:87], 0
	v_mov_b64_e32 v[88:89], 0
	v_mov_b64_e32 v[90:91], 0
	v_mov_b64_e32 v[92:93], 0
	v_mov_b64_e32 v[94:95], 0
	v_mov_b64_e32 v[96:97], 0
	v_mov_b64_e32 v[98:99], 0
	v_mov_b64_e32 v[100:101], 0
	v_mov_b64_e32 v[102:103], 0
	v_mov_b64_e32 v[104:105], 0
	v_mov_b64_e32 v[106:107], 0
	v_mov_b64_e32 v[108:109], 0
	v_mov_b64_e32 v[110:111], 0
	v_mov_b64_e32 v[112:113], 0
	v_mov_b64_e32 v[114:115], 0
	v_mov_b64_e32 v[116:117], 0
	v_mov_b64_e32 v[118:119], 0
	v_mov_b64_e32 v[120:121], 0
	v_mov_b64_e32 v[122:123], 0
	v_mov_b64_e32 v[124:125], 0
	v_mov_b64_e32 v[126:127], 0
	s_and_b64 vcc, exec, s[6:7]
	.p2align 8
	s_cbranch_vccnz .LBB0_634
	s_add_u32 s58, s58, 0x80
	s_addc_u32 s59, s59, 0
	s_add_u32 s33, s60, 0x100
	s_addc_u32 s89, s61, 0
	s_mov_b32 s60, 0

; template <class Epi, class Sched, bool ALIGN_EPI = false, bool SP2 = false>
; __device__ __forceinline__ void gemm_phase(PG8_LAS unsigned char* lds, const Gemm g, const Sched& S, const Epi& E) {
;     ...
; #pragma unroll
;         for (int a = 0; a < 2; ++a)
; #pragma unroll
;             for (int b = 0; b < 2; ++b)
; #pragma unroll
;                 for (int m = 0; m < 4; ++m)
; #pragma unroll
;                     for (int n = 0; n < 2; ++n) acc[a][b][m][n] = (f32x4){0.f, 0.f, 0.f, 0.f};
.LBB0_919:
	v_mov_b64_e32 v[0:1], 0
	v_mov_b64_e32 v[2:3], 0
	v_mov_b64_e32 v[4:5], 0
	v_mov_b64_e32 v[6:7], 0
	v_mov_b64_e32 v[8:9], 0
	v_mov_b64_e32 v[10:11], 0
	v_mov_b64_e32 v[12:13], 0
	v_mov_b64_e32 v[14:15], 0
	v_mov_b64_e32 v[16:17], 0
	v_mov_b64_e32 v[18:19], 0
	v_mov_b64_e32 v[20:21], 0
	v_mov_b64_e32 v[22:23], 0
	v_mov_b64_e32 v[24:25], 0
	v_mov_b64_e32 v[26:27], 0
	v_mov_b64_e32 v[28:29], 0
	v_mov_b64_e32 v[30:31], 0
	v_mov_b64_e32 v[32:33], 0
	v_mov_b64_e32 v[34:35], 0
	v_mov_b64_e32 v[36:37], 0
	v_mov_b64_e32 v[38:39], 0
	v_mov_b64_e32 v[40:41], 0
	v_mov_b64_e32 v[42:43], 0
	v_mov_b64_e32 v[44:45], 0
	v_mov_b64_e32 v[46:47], 0
	v_mov_b64_e32 v[48:49], 0
	v_mov_b64_e32 v[50:51], 0
	v_mov_b64_e32 v[52:53], 0
	v_mov_b64_e32 v[54:55], 0
	v_mov_b64_e32 v[56:57], 0
	v_mov_b64_e32 v[58:59], 0
	v_mov_b64_e32 v[60:61], 0
	v_mov_b64_e32 v[62:63], 0
	v_mov_b64_e32 v[64:65], 0
	v_mov_b64_e32 v[66:67], 0
	v_mov_b64_e32 v[68:69], 0
	v_mov_b64_e32 v[70:71], 0
	v_mov_b64_e32 v[72:73], 0
	v_mov_b64_e32 v[74:75], 0
	v_mov_b64_e32 v[76:77], 0
	v_mov_b64_e32 v[78:79], 0
	v_mov_b64_e32 v[80:81], 0
	v_mov_b64_e32 v[82:83], 0
	v_mov_b64_e32 v[84:85], 0
	v_mov_b64_e32 v[86:87], 0
	v_mov_b64_e32 v[88:89], 0
	v_mov_b64_e32 v[90:91], 0
	v_mov_b64_e32 v[92:93], 0
	v_mov_b64_e32 v[94:95], 0
	v_mov_b64_e32 v[96:97], 0
	v_mov_b64_e32 v[98:99], 0
	v_mov_b64_e32 v[100:101], 0
	v_mov_b64_e32 v[102:103], 0
	v_mov_b64_e32 v[104:105], 0
	v_mov_b64_e32 v[106:107], 0
	v_mov_b64_e32 v[108:109], 0
	v_mov_b64_e32 v[110:111], 0
	v_mov_b64_e32 v[112:113], 0
	v_mov_b64_e32 v[114:115], 0
	v_mov_b64_e32 v[116:117], 0
	v_mov_b64_e32 v[118:119], 0
	v_mov_b64_e32 v[120:121], 0
	v_mov_b64_e32 v[122:123], 0
	v_mov_b64_e32 v[124:125], 0
	v_mov_b64_e32 v[126:127], 0
	s_andn2_b64 vcc, exec, s[36:37]
	s_waitcnt vmcnt(0)
	.p2align 8
	s_cbranch_vccnz .LBB0_922
	s_add_u32 s42, s42, 0x80
	s_addc_u32 s43, s43, 0
	s_add_u32 s5, s58, 0x100
	s_addc_u32 s33, s59, 0
	s_mov_b32 s58, 0

; template <class Epi, class Sched, bool ALIGN_EPI = false, bool SP2 = false>
; __device__ __forceinline__ void gemm_phase(PG8_LAS unsigned char* lds, const Gemm g, const Sched& S, const Epi& E) {
;     ...
; #pragma unroll
;         for (int a = 0; a < 2; ++a)
; #pragma unroll
;             for (int b = 0; b < 2; ++b)
; #pragma unroll
;                 for (int m = 0; m < 4; ++m)
; #pragma unroll
;                     for (int n = 0; n < 2; ++n) acc[a][b][m][n] = (f32x4){0.f, 0.f, 0.f, 0.f};
.LBB0_1012:
	v_mov_b64_e32 v[0:1], 0
	v_mov_b64_e32 v[2:3], 0
	v_mov_b64_e32 v[4:5], 0
	v_mov_b64_e32 v[6:7], 0
	v_mov_b64_e32 v[8:9], 0
	v_mov_b64_e32 v[10:11], 0
	v_mov_b64_e32 v[12:13], 0
	v_mov_b64_e32 v[14:15], 0
	v_mov_b64_e32 v[16:17], 0
	v_mov_b64_e32 v[18:19], 0
	v_mov_b64_e32 v[20:21], 0
	v_mov_b64_e32 v[22:23], 0
	v_mov_b64_e32 v[24:25], 0
	v_mov_b64_e32 v[26:27], 0
	v_mov_b64_e32 v[28:29], 0
	v_mov_b64_e32 v[30:31], 0
	v_mov_b64_e32 v[32:33], 0
	v_mov_b64_e32 v[34:35], 0
	v_mov_b64_e32 v[36:37], 0
	v_mov_b64_e32 v[38:39], 0
	v_mov_b64_e32 v[40:41], 0
	v_mov_b64_e32 v[42:43], 0
	v_mov_b64_e32 v[44:45], 0
	v_mov_b64_e32 v[46:47], 0
	v_mov_b64_e32 v[48:49], 0
	v_mov_b64_e32 v[50:51], 0
	v_mov_b64_e32 v[52:53], 0
	v_mov_b64_e32 v[54:55], 0
	v_mov_b64_e32 v[56:57], 0
	v_mov_b64_e32 v[58:59], 0
	v_mov_b64_e32 v[60:61], 0
	v_mov_b64_e32 v[62:63], 0
	v_mov_b64_e32 v[64:65], 0
	v_mov_b64_e32 v[66:67], 0
	v_mov_b64_e32 v[68:69], 0
	v_mov_b64_e32 v[70:71], 0
	v_mov_b64_e32 v[72:73], 0
	v_mov_b64_e32 v[74:75], 0
	v_mov_b64_e32 v[76:77], 0
	v_mov_b64_e32 v[78:79], 0
	v_mov_b64_e32 v[80:81], 0
	v_mov_b64_e32 v[82:83], 0
	v_mov_b64_e32 v[84:85], 0
	v_mov_b64_e32 v[86:87], 0
	v_mov_b64_e32 v[88:89], 0
	v_mov_b64_e32 v[90:91], 0
	v_mov_b64_e32 v[92:93], 0
	v_mov_b64_e32 v[94:95], 0
	v_mov_b64_e32 v[96:97], 0
	v_mov_b64_e32 v[98:99], 0
	v_mov_b64_e32 v[100:101], 0
	v_mov_b64_e32 v[102:103], 0
	v_mov_b64_e32 v[104:105], 0
	v_mov_b64_e32 v[106:107], 0
	v_mov_b64_e32 v[108:109], 0
	v_mov_b64_e32 v[110:111], 0
	v_mov_b64_e32 v[112:113], 0
	v_mov_b64_e32 v[114:115], 0
	v_mov_b64_e32 v[116:117], 0
	v_mov_b64_e32 v[118:119], 0
	v_mov_b64_e32 v[120:121], 0
	v_mov_b64_e32 v[122:123], 0
	v_mov_b64_e32 v[124:125], 0
	v_mov_b64_e32 v[126:127], 0
	s_andn2_b64 vcc, exec, s[18:19]
	s_waitcnt vmcnt(0)
	.p2align 8
	s_cbranch_vccnz .LBB0_1015
	s_add_u32 s36, s36, 0x80
	s_addc_u32 s37, s37, 0
	s_add_u32 s33, s38, 0x100
	s_addc_u32 s70, s39, 0
	s_mov_b32 s38, 0

; template <class Epi, class Sched, bool ALIGN_EPI = false, bool SP2 = false>
; __device__ __forceinline__ void gemm_phase(PG8_LAS unsigned char* lds, const Gemm g, const Sched& S, const Epi& E) {
;     ...
; #pragma unroll
;         for (int a = 0; a < 2; ++a)
; #pragma unroll
;             for (int b = 0; b < 2; ++b)
; #pragma unroll
;                 for (int m = 0; m < 4; ++m)
; #pragma unroll
;                     for (int n = 0; n < 2; ++n) acc[a][b][m][n] = (f32x4){0.f, 0.f, 0.f, 0.f};
.LBB0_1032:
	v_mov_b64_e32 v[0:1], 0
	v_mov_b64_e32 v[2:3], 0
	v_mov_b64_e32 v[4:5], 0
	v_mov_b64_e32 v[6:7], 0
	v_mov_b64_e32 v[8:9], 0
	v_mov_b64_e32 v[10:11], 0
	v_mov_b64_e32 v[12:13], 0
	v_mov_b64_e32 v[14:15], 0
	v_mov_b64_e32 v[16:17], 0
	v_mov_b64_e32 v[18:19], 0
	v_mov_b64_e32 v[20:21], 0
	v_mov_b64_e32 v[22:23], 0
	v_mov_b64_e32 v[24:25], 0
	v_mov_b64_e32 v[26:27], 0
	v_mov_b64_e32 v[28:29], 0
	v_mov_b64_e32 v[30:31], 0
	v_mov_b64_e32 v[32:33], 0
	v_mov_b64_e32 v[34:35], 0
	v_mov_b64_e32 v[36:37], 0
	v_mov_b64_e32 v[38:39], 0
	v_mov_b64_e32 v[40:41], 0
	v_mov_b64_e32 v[42:43], 0
	v_mov_b64_e32 v[44:45], 0
	v_mov_b64_e32 v[46:47], 0
	v_mov_b64_e32 v[48:49], 0
	v_mov_b64_e32 v[50:51], 0
	v_mov_b64_e32 v[52:53], 0
	v_mov_b64_e32 v[54:55], 0
	v_mov_b64_e32 v[56:57], 0
	v_mov_b64_e32 v[58:59], 0
	v_mov_b64_e32 v[60:61], 0
	v_mov_b64_e32 v[62:63], 0
	v_mov_b64_e32 v[64:65], 0
	v_mov_b64_e32 v[66:67], 0
	v_mov_b64_e32 v[68:69], 0
	v_mov_b64_e32 v[70:71], 0
	v_mov_b64_e32 v[72:73], 0
	v_mov_b64_e32 v[74:75], 0
	v_mov_b64_e32 v[76:77], 0
	v_mov_b64_e32 v[78:79], 0
	v_mov_b64_e32 v[80:81], 0
	v_mov_b64_e32 v[82:83], 0
	v_mov_b64_e32 v[84:85], 0
	v_mov_b64_e32 v[86:87], 0
	v_mov_b64_e32 v[88:89], 0
	v_mov_b64_e32 v[90:91], 0
	v_mov_b64_e32 v[92:93], 0
	v_mov_b64_e32 v[94:95], 0
	v_mov_b64_e32 v[96:97], 0
	v_mov_b64_e32 v[98:99], 0
	v_mov_b64_e32 v[100:101], 0
	v_mov_b64_e32 v[102:103], 0
	v_mov_b64_e32 v[104:105], 0
	v_mov_b64_e32 v[106:107], 0
	v_mov_b64_e32 v[108:109], 0
	v_mov_b64_e32 v[110:111], 0
	v_mov_b64_e32 v[112:113], 0
	v_mov_b64_e32 v[114:115], 0
	v_mov_b64_e32 v[116:117], 0
	v_mov_b64_e32 v[118:119], 0
	v_mov_b64_e32 v[120:121], 0
	v_mov_b64_e32 v[122:123], 0
	v_mov_b64_e32 v[124:125], 0
	v_mov_b64_e32 v[126:127], 0
	s_and_b64 vcc, exec, s[0:1]
	.p2align 8
	s_cbranch_vccnz .LBB0_1035
	s_add_u32 s54, s54, 0x80
	s_addc_u32 s55, s55, 0
	s_add_u32 s33, s56, 0x100
	s_addc_u32 s85, s57, 0
	s_mov_b32 s56, 0

; template <class Epi, class Sched, bool ALIGN_EPI = false, bool SP2 = false>
; __device__ __forceinline__ void gemm_phase(PG8_LAS unsigned char* lds, const Gemm g, const Sched& S, const Epi& E) {
;     ...
; #pragma unroll
;         for (int a = 0; a < 2; ++a)
; #pragma unroll
;             for (int b = 0; b < 2; ++b)
; #pragma unroll
;                 for (int m = 0; m < 4; ++m)
; #pragma unroll
;                     for (int n = 0; n < 2; ++n) acc[a][b][m][n] = (f32x4){0.f, 0.f, 0.f, 0.f};
.LBB0_1219:
	v_mov_b64_e32 v[0:1], 0
	v_mov_b64_e32 v[2:3], 0
	v_mov_b64_e32 v[4:5], 0
	v_mov_b64_e32 v[6:7], 0
	v_mov_b64_e32 v[8:9], 0
	v_mov_b64_e32 v[10:11], 0
	v_mov_b64_e32 v[12:13], 0
	v_mov_b64_e32 v[14:15], 0
	v_mov_b64_e32 v[16:17], 0
	v_mov_b64_e32 v[18:19], 0
	v_mov_b64_e32 v[20:21], 0
	v_mov_b64_e32 v[22:23], 0
	v_mov_b64_e32 v[24:25], 0
	v_mov_b64_e32 v[26:27], 0
	v_mov_b64_e32 v[28:29], 0
	v_mov_b64_e32 v[30:31], 0
	v_mov_b64_e32 v[32:33], 0
	v_mov_b64_e32 v[34:35], 0
	v_mov_b64_e32 v[36:37], 0
	v_mov_b64_e32 v[38:39], 0
	v_mov_b64_e32 v[40:41], 0
	v_mov_b64_e32 v[42:43], 0
	v_mov_b64_e32 v[44:45], 0
	v_mov_b64_e32 v[46:47], 0
	v_mov_b64_e32 v[48:49], 0
	v_mov_b64_e32 v[50:51], 0
	v_mov_b64_e32 v[52:53], 0
	v_mov_b64_e32 v[54:55], 0
	v_mov_b64_e32 v[56:57], 0
	v_mov_b64_e32 v[58:59], 0
	v_mov_b64_e32 v[60:61], 0
	v_mov_b64_e32 v[62:63], 0
	v_mov_b64_e32 v[64:65], 0
	v_mov_b64_e32 v[66:67], 0
	v_mov_b64_e32 v[68:69], 0
	v_mov_b64_e32 v[70:71], 0
	v_mov_b64_e32 v[72:73], 0
	v_mov_b64_e32 v[74:75], 0
	v_mov_b64_e32 v[76:77], 0
	v_mov_b64_e32 v[78:79], 0
	v_mov_b64_e32 v[80:81], 0
	v_mov_b64_e32 v[82:83], 0
	v_mov_b64_e32 v[84:85], 0
	v_mov_b64_e32 v[86:87], 0
	v_mov_b64_e32 v[88:89], 0
	v_mov_b64_e32 v[90:91], 0
	v_mov_b64_e32 v[92:93], 0
	v_mov_b64_e32 v[94:95], 0
	v_mov_b64_e32 v[96:97], 0
	v_mov_b64_e32 v[98:99], 0
	v_mov_b64_e32 v[100:101], 0
	v_mov_b64_e32 v[102:103], 0
	v_mov_b64_e32 v[104:105], 0
	v_mov_b64_e32 v[106:107], 0
	v_mov_b64_e32 v[108:109], 0
	v_mov_b64_e32 v[110:111], 0
	v_mov_b64_e32 v[112:113], 0
	v_mov_b64_e32 v[114:115], 0
	v_mov_b64_e32 v[116:117], 0
	v_mov_b64_e32 v[118:119], 0
	v_mov_b64_e32 v[120:121], 0
	v_mov_b64_e32 v[122:123], 0
	v_mov_b64_e32 v[124:125], 0
	v_mov_b64_e32 v[126:127], 0
	s_andn2_b64 vcc, exec, s[18:19]
	.p2align 8
	s_cbranch_vccnz .LBB0_1222
	s_add_u32 s42, s42, 0x80
	s_addc_u32 s43, s43, 0
	s_add_u32 s68, s48, 0x100
	s_addc_u32 s69, s49, 0
	s_mov_b32 s48, 0
